# scanner loop back edge rotated: exit and warm-up tests moved in front of the interval barrier so the chunk starts its LDS reads right after the barrier
# speedup vs baseline: 1.0130x; 1.0040x over previous
; #define LAS __attribute__((address_space(3)))
; __device__ __forceinline__ float allred16(float x) { x += dpp_f<0xB1>(x); x += dpp_f<0x4E>(x); x += dpp_f<0x141>(x); x += dpp_f<0x140>(x); return x; }
; #define SCAN_BAR() do { asm volatile("s_waitcnt lgkmcnt(0)" ::: "memory"); __builtin_amdgcn_s_barrier(); asm volatile("" ::: "memory"); } while (0)
; __device__ __forceinline__ void phase_scan(const Args& a, int l, LAS unsigned char* lds) {
;     ...
;             for (int it = -6; it < NCH; ++it) {
;                 if (it >= 0) {
;                     const LAS float* tb = buf + (it % NB) * TC * TOKF;
;                     LAS float* yb = ybuf + (it & 1) * TC * 16;
;                     f32x4 w = *(const LAS f32x4*)(tb + 4 * j), kk = *(const LAS f32x4*)(tb + 64 + 4 * j), bv = *(const LAS f32x4*)(tb + 128 + 4 * j);
;                     f32x4 kv = *(const LAS f32x4*)(tb + 192 + 4 * j), wr = *(const LAS f32x4*)(tb + 256 + 4 * j);
;                     float vv = tb[320 + rowl];
;                     float yv = 0.f;
; #pragma unroll
;                     for (int t = 0; t < TC; ++t) {
;                         f32x4 nw = w, nkk = kk, nbv = bv, nkv = kv, nwr = wr; float nvv = vv;
;                         if (t + 1 < TC) { const LAS float* p = tb + (t + 1) * TOKF;
;                             nw = *(const LAS f32x4*)(p + 4 * j); nkk = *(const LAS f32x4*)(p + 64 + 4 * j); nbv = *(const LAS f32x4*)(p + 128 + 4 * j);
;                             nkv = *(const LAS f32x4*)(p + 192 + 4 * j); nwr = *(const LAS f32x4*)(p + 256 + 4 * j); nvv = p[320 + rowl]; }
;                         f32x2 ta = Sl * kk.lo; ta = Sh * kk.hi + ta;
;                         float pa = ta.x + ta.y;
;                         const f32x2 tl = Sl * w.lo + kv.lo * vv, th = Sh * w.hi + kv.hi * vv;
;                         pa = allred16(pa);
;                         Sl = bv.lo * pa + tl;
;                         Sh = bv.hi * pa + th;
;                         f32x2 ty = Sl * wr.lo; ty = Sh * wr.hi + ty;
;                         float y = ty.x + ty.y;
;                         y = allred16(y);
;                         yv = (j == t) ? y : yv;
;                         w = nw; kk = nkk; bv = nbv; kv = nkv; wr = nwr; vv = nvv;
;                     }
;                     yb[j * 16 + rowl] = yv;
;                 }
;                 SCAN_BAR();
.LBB0_167:
	s_add_i32 s0, s0, 1
	s_addk_i32 s1, 0x100
	s_and_b32 s38, s0, 0xff
	s_mulk_i32 s38, 0xcd
	s_lshr_b32 s38, s38, 10
	s_mul_i32 s38, s38, 5
	s_sub_i32 s38, s0, s38
	s_and_b32 s38, s38, 0xff
	s_mulk_i32 s38, 0x5500
	v_lshl_add_u32 v50, v192, 2, s38
	v_lshl_add_u32 v51, v103, 2, s38
	s_and_b32 s38, s1, 0x100
	s_cmpk_eq_i32 s0, 0x100
	s_cbranch_scc1 .Lscan_exit_bar
	s_cmp_lt_i32 s0, 0
	s_cbranch_scc1 .Lscan_warm_bar
	s_waitcnt lgkmcnt(0)
	s_barrier
.LBB0_168:
	ds_read_b128 v[10:13], v50 offset:256
	ds_read_b128 v[6:9], v50 offset:0
	ds_read_b128 v[18:21], v50 offset:768
	ds_read_b32 v26, v51 offset:1280
	ds_read_b128 v[14:17], v50 offset:512
	ds_read_b128 v[22:25], v50 offset:1024
	ds_read_b128 v[32:35], v50 offset:1616
	ds_read_b128 v[28:31], v50 offset:1360
	ds_read_b128 v[40:43], v50 offset:2128
	ds_read_b32 v48, v51 offset:2640
	ds_read_b128 v[36:39], v50 offset:1872
	ds_read_b128 v[44:47], v50 offset:2384
	s_waitcnt lgkmcnt(6)
	v_pk_mul_f32 v[76:77], v[2:3], v[10:11]
	ds_read_b128 v[58:61], v50 offset:2976
	v_pk_fma_f32 v[76:77], v[4:5], v[12:13], v[76:77]
	v_pk_mul_f32 v[80:81], v[18:19], v[26:27] op_sel_hi:[1,0]
	v_add_f32_e32 v78, v76, v77
	v_pk_mul_f32 v[82:83], v[20:21], v[26:27] op_sel_hi:[1,0]
	s_nop 0
	v_add_f32_dpp v78, v78, v78 quad_perm:[1,0,3,2] row_mask:0xf bank_mask:0xf bound_ctrl:1
	v_pk_fma_f32 v[80:81], v[2:3], v[6:7], v[80:81]
	s_nop 0
	v_add_f32_dpp v78, v78, v78 quad_perm:[2,3,0,1] row_mask:0xf bank_mask:0xf bound_ctrl:1
	v_pk_fma_f32 v[82:83], v[4:5], v[8:9], v[82:83]
	s_nop 0
	v_add_f32_dpp v78, v78, v78 row_half_mirror row_mask:0xf bank_mask:0xf bound_ctrl:1
	ds_read_b128 v[54:57], v50 offset:2720
	ds_read_b128 v[66:69], v50 offset:3488
	v_add_f32_dpp v78, v78, v78 row_mirror row_mask:0xf bank_mask:0xf bound_ctrl:1
	v_pk_fma_f32 v[2:3], v[14:15], v[78:79], v[80:81] op_sel_hi:[1,0,1]
	v_pk_fma_f32 v[4:5], v[16:17], v[78:79], v[82:83] op_sel_hi:[1,0,1]
	ds_read_b32 v74, v51 offset:4000
	ds_read_b128 v[62:65], v50 offset:3232
	ds_read_b128 v[70:73], v50 offset:3744
	s_waitcnt lgkmcnt(6)
	v_pk_mul_f32 v[76:77], v[2:3], v[32:33]
	ds_read_b128 v[108:111], v50 offset:4336
	v_pk_fma_f32 v[76:77], v[4:5], v[34:35], v[76:77]
	v_pk_mul_f32 v[80:81], v[40:41], v[48:49] op_sel_hi:[1,0]
	v_add_f32_e32 v78, v76, v77
	v_pk_mul_f32 v[82:83], v[42:43], v[48:49] op_sel_hi:[1,0]
	v_pk_mul_f32 v[84:85], v[22:23], v[2:3]
	v_add_f32_dpp v78, v78, v78 quad_perm:[1,0,3,2] row_mask:0xf bank_mask:0xf bound_ctrl:1
	v_pk_fma_f32 v[84:85], v[24:25], v[4:5], v[84:85]
	v_pk_fma_f32 v[80:81], v[2:3], v[28:29], v[80:81]
	v_add_f32_dpp v78, v78, v78 quad_perm:[2,3,0,1] row_mask:0xf bank_mask:0xf bound_ctrl:1
	v_add_f32_e32 v86, v84, v85
	v_pk_fma_f32 v[82:83], v[4:5], v[30:31], v[82:83]
	v_add_f32_dpp v78, v78, v78 row_half_mirror row_mask:0xf bank_mask:0xf bound_ctrl:1
	ds_read_b128 v[104:107], v50 offset:4080
	ds_read_b128 v[116:119], v50 offset:4848
	v_add_f32_dpp v78, v78, v78 row_mirror row_mask:0xf bank_mask:0xf bound_ctrl:1
	v_pk_fma_f32 v[2:3], v[36:37], v[78:79], v[80:81] op_sel_hi:[1,0,1]
	v_pk_fma_f32 v[4:5], v[38:39], v[78:79], v[82:83] op_sel_hi:[1,0,1]
	ds_read_b32 v124, v51 offset:5360
	ds_read_b128 v[112:115], v50 offset:4592
	ds_read_b128 v[120:123], v50 offset:5104
	s_waitcnt lgkmcnt(6)
	v_pk_mul_f32 v[76:77], v[2:3], v[58:59]
	ds_read_b128 v[10:13], v50 offset:5696
	v_pk_fma_f32 v[76:77], v[4:5], v[60:61], v[76:77]
	v_pk_mul_f32 v[80:81], v[66:67], v[74:75] op_sel_hi:[1,0]
	v_add_f32_e32 v78, v76, v77
	v_pk_mul_f32 v[82:83], v[68:69], v[74:75] op_sel_hi:[1,0]
	v_pk_mul_f32 v[84:85], v[44:45], v[2:3]
	v_add_f32_dpp v78, v78, v78 quad_perm:[1,0,3,2] row_mask:0xf bank_mask:0xf bound_ctrl:1
	v_pk_fma_f32 v[84:85], v[46:47], v[4:5], v[84:85]
	v_pk_fma_f32 v[80:81], v[2:3], v[54:55], v[80:81]
	v_add_f32_dpp v78, v78, v78 quad_perm:[2,3,0,1] row_mask:0xf bank_mask:0xf bound_ctrl:1
	v_add_f32_e32 v87, v84, v85
	v_pk_fma_f32 v[82:83], v[4:5], v[56:57], v[82:83]
	v_add_f32_dpp v78, v78, v78 row_half_mirror row_mask:0xf bank_mask:0xf bound_ctrl:1
	ds_read_b128 v[6:9], v50 offset:5440
	ds_read_b128 v[18:21], v50 offset:6208
	v_add_f32_dpp v78, v78, v78 row_mirror row_mask:0xf bank_mask:0xf bound_ctrl:1
	v_pk_fma_f32 v[2:3], v[62:63], v[78:79], v[80:81] op_sel_hi:[1,0,1]
	v_pk_fma_f32 v[4:5], v[64:65], v[78:79], v[82:83] op_sel_hi:[1,0,1]
	ds_read_b32 v26, v51 offset:6720
	ds_read_b128 v[14:17], v50 offset:5952
	ds_read_b128 v[22:25], v50 offset:6464
	s_waitcnt lgkmcnt(6)
	v_pk_mul_f32 v[76:77], v[2:3], v[108:109]
	ds_read_b128 v[32:35], v50 offset:7056
	v_pk_fma_f32 v[76:77], v[4:5], v[110:111], v[76:77]
	v_pk_mul_f32 v[80:81], v[116:117], v[124:125] op_sel_hi:[1,0]
	v_add_f32_e32 v78, v76, v77
	v_pk_mul_f32 v[82:83], v[118:119], v[124:125] op_sel_hi:[1,0]
	v_pk_mul_f32 v[84:85], v[70:71], v[2:3]
	v_add_f32_dpp v78, v78, v78 quad_perm:[1,0,3,2] row_mask:0xf bank_mask:0xf bound_ctrl:1
	v_pk_fma_f32 v[84:85], v[72:73], v[4:5], v[84:85]
	v_pk_fma_f32 v[80:81], v[2:3], v[104:105], v[80:81]
	v_add_f32_dpp v78, v78, v78 quad_perm:[2,3,0,1] row_mask:0xf bank_mask:0xf bound_ctrl:1
	v_add_f32_e32 v88, v84, v85
	v_pk_fma_f32 v[82:83], v[4:5], v[106:107], v[82:83]
	v_add_f32_dpp v78, v78, v78 row_half_mirror row_mask:0xf bank_mask:0xf bound_ctrl:1
	ds_read_b128 v[28:31], v50 offset:6800
	ds_read_b128 v[40:43], v50 offset:7568
	v_add_f32_dpp v78, v78, v78 row_mirror row_mask:0xf bank_mask:0xf bound_ctrl:1
	v_pk_fma_f32 v[2:3], v[112:113], v[78:79], v[80:81] op_sel_hi:[1,0,1]
	v_pk_fma_f32 v[4:5], v[114:115], v[78:79], v[82:83] op_sel_hi:[1,0,1]
	ds_read_b32 v48, v51 offset:8080
	ds_read_b128 v[36:39], v50 offset:7312
	ds_read_b128 v[44:47], v50 offset:7824
	s_waitcnt lgkmcnt(6)
; #define LAS __attribute__((address_space(3)))
; __device__ __forceinline__ float allred16(float x) { x += dpp_f<0xB1>(x); x += dpp_f<0x4E>(x); x += dpp_f<0x141>(x); x += dpp_f<0x140>(x); return x; }
; __device__ __forceinline__ void phase_scan(const Args& a, int l, LAS unsigned char* lds) {
;     ...
;                     for (int t = 0; t < TC; ++t) {
;                         f32x4 nw = w, nkk = kk, nbv = bv, nkv = kv, nwr = wr; float nvv = vv;
;                         if (t + 1 < TC) { const LAS float* p = tb + (t + 1) * TOKF;
;                             nw = *(const LAS f32x4*)(p + 4 * j); nkk = *(const LAS f32x4*)(p + 64 + 4 * j); nbv = *(const LAS f32x4*)(p + 128 + 4 * j);
;                             nkv = *(const LAS f32x4*)(p + 192 + 4 * j); nwr = *(const LAS f32x4*)(p + 256 + 4 * j); nvv = p[320 + rowl]; }
;                         f32x2 ta = Sl * kk.lo; ta = Sh * kk.hi + ta;
;                         float pa = ta.x + ta.y;
;                         const f32x2 tl = Sl * w.lo + kv.lo * vv, th = Sh * w.hi + kv.hi * vv;
;                         pa = allred16(pa);
;                         Sl = bv.lo * pa + tl;
;                         Sh = bv.hi * pa + th;
;                         f32x2 ty = Sl * wr.lo; ty = Sh * wr.hi + ty;
;                         float y = ty.x + ty.y;
;                         y = allred16(y);
;                         yv = (j == t) ? y : yv;
;                         w = nw; kk = nkk; bv = nbv; kv = nkv; wr = nwr; vv = nvv;
;                     }
	v_pk_mul_f32 v[76:77], v[2:3], v[10:11]
	ds_read_b128 v[58:61], v50 offset:8416
	v_pk_fma_f32 v[76:77], v[4:5], v[12:13], v[76:77]
	v_pk_mul_f32 v[80:81], v[18:19], v[26:27] op_sel_hi:[1,0]
	v_add_f32_e32 v78, v76, v77
	v_pk_mul_f32 v[82:83], v[20:21], v[26:27] op_sel_hi:[1,0]
	v_pk_mul_f32 v[84:85], v[120:121], v[2:3]
	v_add_f32_dpp v78, v78, v78 quad_perm:[1,0,3,2] row_mask:0xf bank_mask:0xf bound_ctrl:1
	v_pk_fma_f32 v[84:85], v[122:123], v[4:5], v[84:85]
	v_pk_fma_f32 v[80:81], v[2:3], v[6:7], v[80:81]
	v_add_f32_dpp v78, v78, v78 quad_perm:[2,3,0,1] row_mask:0xf bank_mask:0xf bound_ctrl:1
	v_add_f32_e32 v89, v84, v85
	v_pk_fma_f32 v[82:83], v[4:5], v[8:9], v[82:83]
	v_add_f32_dpp v78, v78, v78 row_half_mirror row_mask:0xf bank_mask:0xf bound_ctrl:1
	ds_read_b128 v[54:57], v50 offset:8160
	ds_read_b128 v[66:69], v50 offset:8928
	v_add_f32_dpp v78, v78, v78 row_mirror row_mask:0xf bank_mask:0xf bound_ctrl:1
	v_pk_fma_f32 v[2:3], v[14:15], v[78:79], v[80:81] op_sel_hi:[1,0,1]
	v_pk_fma_f32 v[4:5], v[16:17], v[78:79], v[82:83] op_sel_hi:[1,0,1]
	ds_read_b32 v74, v51 offset:9440
	ds_read_b128 v[62:65], v50 offset:8672
	ds_read_b128 v[70:73], v50 offset:9184
	s_waitcnt lgkmcnt(6)
	v_pk_mul_f32 v[76:77], v[2:3], v[32:33]
	ds_read_b128 v[108:111], v50 offset:9776
	v_pk_fma_f32 v[76:77], v[4:5], v[34:35], v[76:77]
	v_pk_mul_f32 v[80:81], v[40:41], v[48:49] op_sel_hi:[1,0]
	v_add_f32_e32 v78, v76, v77
	v_pk_mul_f32 v[82:83], v[42:43], v[48:49] op_sel_hi:[1,0]
	v_pk_mul_f32 v[84:85], v[22:23], v[2:3]
	v_add_f32_dpp v78, v78, v78 quad_perm:[1,0,3,2] row_mask:0xf bank_mask:0xf bound_ctrl:1
	v_pk_fma_f32 v[84:85], v[24:25], v[4:5], v[84:85]
	v_pk_fma_f32 v[80:81], v[2:3], v[28:29], v[80:81]
	v_add_f32_dpp v78, v78, v78 quad_perm:[2,3,0,1] row_mask:0xf bank_mask:0xf bound_ctrl:1
	v_add_f32_e32 v90, v84, v85
	v_pk_fma_f32 v[82:83], v[4:5], v[30:31], v[82:83]
	v_add_f32_dpp v78, v78, v78 row_half_mirror row_mask:0xf bank_mask:0xf bound_ctrl:1
	ds_read_b128 v[104:107], v50 offset:9520
	ds_read_b128 v[116:119], v50 offset:10288
	v_add_f32_dpp v78, v78, v78 row_mirror row_mask:0xf bank_mask:0xf bound_ctrl:1
	v_pk_fma_f32 v[2:3], v[36:37], v[78:79], v[80:81] op_sel_hi:[1,0,1]
	v_pk_fma_f32 v[4:5], v[38:39], v[78:79], v[82:83] op_sel_hi:[1,0,1]
	ds_read_b32 v124, v51 offset:10800
	ds_read_b128 v[112:115], v50 offset:10032
	ds_read_b128 v[120:123], v50 offset:10544
	s_waitcnt lgkmcnt(6)
	v_pk_mul_f32 v[76:77], v[2:3], v[58:59]
	ds_read_b128 v[10:13], v50 offset:11136
	v_pk_fma_f32 v[76:77], v[4:5], v[60:61], v[76:77]
	v_pk_mul_f32 v[80:81], v[66:67], v[74:75] op_sel_hi:[1,0]
	v_add_f32_e32 v78, v76, v77
	v_pk_mul_f32 v[82:83], v[68:69], v[74:75] op_sel_hi:[1,0]
	v_pk_mul_f32 v[84:85], v[44:45], v[2:3]
	v_add_f32_dpp v78, v78, v78 quad_perm:[1,0,3,2] row_mask:0xf bank_mask:0xf bound_ctrl:1
	v_pk_fma_f32 v[84:85], v[46:47], v[4:5], v[84:85]
	v_pk_fma_f32 v[80:81], v[2:3], v[54:55], v[80:81]
	v_add_f32_dpp v78, v78, v78 quad_perm:[2,3,0,1] row_mask:0xf bank_mask:0xf bound_ctrl:1
	v_add_f32_e32 v91, v84, v85
	v_pk_fma_f32 v[82:83], v[4:5], v[56:57], v[82:83]
	v_add_f32_dpp v78, v78, v78 row_half_mirror row_mask:0xf bank_mask:0xf bound_ctrl:1
	ds_read_b128 v[6:9], v50 offset:10880
	ds_read_b128 v[18:21], v50 offset:11648
	v_add_f32_dpp v78, v78, v78 row_mirror row_mask:0xf bank_mask:0xf bound_ctrl:1
	v_pk_fma_f32 v[2:3], v[62:63], v[78:79], v[80:81] op_sel_hi:[1,0,1]
	v_pk_fma_f32 v[4:5], v[64:65], v[78:79], v[82:83] op_sel_hi:[1,0,1]
	ds_read_b32 v26, v51 offset:12160
	ds_read_b128 v[14:17], v50 offset:11392
	ds_read_b128 v[22:25], v50 offset:11904
	s_waitcnt lgkmcnt(6)
	v_pk_mul_f32 v[76:77], v[2:3], v[108:109]
	ds_read_b128 v[32:35], v50 offset:12496
	v_pk_fma_f32 v[76:77], v[4:5], v[110:111], v[76:77]
	v_pk_mul_f32 v[80:81], v[116:117], v[124:125] op_sel_hi:[1,0]
	v_add_f32_e32 v78, v76, v77
	v_pk_mul_f32 v[82:83], v[118:119], v[124:125] op_sel_hi:[1,0]
	v_pk_mul_f32 v[84:85], v[70:71], v[2:3]
	v_add_f32_dpp v78, v78, v78 quad_perm:[1,0,3,2] row_mask:0xf bank_mask:0xf bound_ctrl:1
	v_pk_fma_f32 v[84:85], v[72:73], v[4:5], v[84:85]
	v_pk_fma_f32 v[80:81], v[2:3], v[104:105], v[80:81]
	v_add_f32_dpp v78, v78, v78 quad_perm:[2,3,0,1] row_mask:0xf bank_mask:0xf bound_ctrl:1
	v_add_f32_e32 v92, v84, v85
	v_pk_fma_f32 v[82:83], v[4:5], v[106:107], v[82:83]
	v_add_f32_dpp v78, v78, v78 row_half_mirror row_mask:0xf bank_mask:0xf bound_ctrl:1
	ds_read_b128 v[28:31], v50 offset:12240
	ds_read_b128 v[40:43], v50 offset:13008
	v_add_f32_dpp v78, v78, v78 row_mirror row_mask:0xf bank_mask:0xf bound_ctrl:1
	v_pk_fma_f32 v[2:3], v[112:113], v[78:79], v[80:81] op_sel_hi:[1,0,1]
	v_pk_fma_f32 v[4:5], v[114:115], v[78:79], v[82:83] op_sel_hi:[1,0,1]
	ds_read_b32 v48, v51 offset:13520
	ds_read_b128 v[36:39], v50 offset:12752
	ds_read_b128 v[44:47], v50 offset:13264
	s_waitcnt lgkmcnt(6)
	v_pk_mul_f32 v[76:77], v[2:3], v[10:11]
	ds_read_b128 v[58:61], v50 offset:13856
	v_pk_fma_f32 v[76:77], v[4:5], v[12:13], v[76:77]
	v_pk_mul_f32 v[80:81], v[18:19], v[26:27] op_sel_hi:[1,0]
	v_add_f32_e32 v78, v76, v77
	v_pk_mul_f32 v[82:83], v[20:21], v[26:27] op_sel_hi:[1,0]
	v_pk_mul_f32 v[84:85], v[120:121], v[2:3]
	v_add_f32_dpp v78, v78, v78 quad_perm:[1,0,3,2] row_mask:0xf bank_mask:0xf bound_ctrl:1
	v_pk_fma_f32 v[84:85], v[122:123], v[4:5], v[84:85]
	v_pk_fma_f32 v[80:81], v[2:3], v[6:7], v[80:81]
	v_add_f32_dpp v78, v78, v78 quad_perm:[2,3,0,1] row_mask:0xf bank_mask:0xf bound_ctrl:1
	v_add_f32_e32 v93, v84, v85
	v_pk_fma_f32 v[82:83], v[4:5], v[8:9], v[82:83]
	v_add_f32_dpp v78, v78, v78 row_half_mirror row_mask:0xf bank_mask:0xf bound_ctrl:1
	ds_read_b128 v[54:57], v50 offset:13600
	ds_read_b128 v[66:69], v50 offset:14368
	v_add_f32_dpp v78, v78, v78 row_mirror row_mask:0xf bank_mask:0xf bound_ctrl:1
	v_pk_fma_f32 v[2:3], v[14:15], v[78:79], v[80:81] op_sel_hi:[1,0,1]
	v_pk_fma_f32 v[4:5], v[16:17], v[78:79], v[82:83] op_sel_hi:[1,0,1]
	ds_read_b32 v74, v51 offset:14880
	ds_read_b128 v[62:65], v50 offset:14112
	ds_read_b128 v[70:73], v50 offset:14624
	s_waitcnt lgkmcnt(6)
; #define LAS __attribute__((address_space(3)))
; __device__ __forceinline__ float allred16(float x) { x += dpp_f<0xB1>(x); x += dpp_f<0x4E>(x); x += dpp_f<0x141>(x); x += dpp_f<0x140>(x); return x; }
; __device__ __forceinline__ void phase_scan(const Args& a, int l, LAS unsigned char* lds) {
;     ...
;                     for (int t = 0; t < TC; ++t) {
;                         f32x4 nw = w, nkk = kk, nbv = bv, nkv = kv, nwr = wr; float nvv = vv;
;                         if (t + 1 < TC) { const LAS float* p = tb + (t + 1) * TOKF;
;                             nw = *(const LAS f32x4*)(p + 4 * j); nkk = *(const LAS f32x4*)(p + 64 + 4 * j); nbv = *(const LAS f32x4*)(p + 128 + 4 * j);
;                             nkv = *(const LAS f32x4*)(p + 192 + 4 * j); nwr = *(const LAS f32x4*)(p + 256 + 4 * j); nvv = p[320 + rowl]; }
;                         f32x2 ta = Sl * kk.lo; ta = Sh * kk.hi + ta;
;                         float pa = ta.x + ta.y;
;                         const f32x2 tl = Sl * w.lo + kv.lo * vv, th = Sh * w.hi + kv.hi * vv;
;                         pa = allred16(pa);
;                         Sl = bv.lo * pa + tl;
;                         Sh = bv.hi * pa + th;
;                         f32x2 ty = Sl * wr.lo; ty = Sh * wr.hi + ty;
;                         float y = ty.x + ty.y;
;                         y = allred16(y);
;                         yv = (j == t) ? y : yv;
;                         w = nw; kk = nkk; bv = nbv; kv = nkv; wr = nwr; vv = nvv;
;                     }
	v_pk_mul_f32 v[76:77], v[2:3], v[32:33]
	ds_read_b128 v[108:111], v50 offset:15216
	v_pk_fma_f32 v[76:77], v[4:5], v[34:35], v[76:77]
	v_pk_mul_f32 v[80:81], v[40:41], v[48:49] op_sel_hi:[1,0]
	v_add_f32_e32 v78, v76, v77
	v_pk_mul_f32 v[82:83], v[42:43], v[48:49] op_sel_hi:[1,0]
	v_pk_mul_f32 v[84:85], v[22:23], v[2:3]
	v_add_f32_dpp v78, v78, v78 quad_perm:[1,0,3,2] row_mask:0xf bank_mask:0xf bound_ctrl:1
	v_pk_fma_f32 v[84:85], v[24:25], v[4:5], v[84:85]
	v_pk_fma_f32 v[80:81], v[2:3], v[28:29], v[80:81]
	v_add_f32_dpp v78, v78, v78 quad_perm:[2,3,0,1] row_mask:0xf bank_mask:0xf bound_ctrl:1
	v_add_f32_e32 v94, v84, v85
	v_pk_fma_f32 v[82:83], v[4:5], v[30:31], v[82:83]
	v_add_f32_dpp v78, v78, v78 row_half_mirror row_mask:0xf bank_mask:0xf bound_ctrl:1
	ds_read_b128 v[104:107], v50 offset:14960
	ds_read_b128 v[116:119], v50 offset:15728
	v_add_f32_dpp v78, v78, v78 row_mirror row_mask:0xf bank_mask:0xf bound_ctrl:1
	v_pk_fma_f32 v[2:3], v[36:37], v[78:79], v[80:81] op_sel_hi:[1,0,1]
	v_pk_fma_f32 v[4:5], v[38:39], v[78:79], v[82:83] op_sel_hi:[1,0,1]
	ds_read_b32 v124, v51 offset:16240
	ds_read_b128 v[112:115], v50 offset:15472
	ds_read_b128 v[120:123], v50 offset:15984
	s_waitcnt lgkmcnt(6)
	v_pk_mul_f32 v[76:77], v[2:3], v[58:59]
	ds_read_b128 v[10:13], v50 offset:16576
	v_pk_fma_f32 v[76:77], v[4:5], v[60:61], v[76:77]
	v_pk_mul_f32 v[80:81], v[66:67], v[74:75] op_sel_hi:[1,0]
	v_add_f32_e32 v78, v76, v77
	v_pk_mul_f32 v[82:83], v[68:69], v[74:75] op_sel_hi:[1,0]
	v_pk_mul_f32 v[84:85], v[44:45], v[2:3]
	v_add_f32_dpp v78, v78, v78 quad_perm:[1,0,3,2] row_mask:0xf bank_mask:0xf bound_ctrl:1
	v_pk_fma_f32 v[84:85], v[46:47], v[4:5], v[84:85]
	v_pk_fma_f32 v[80:81], v[2:3], v[54:55], v[80:81]
	v_add_f32_dpp v78, v78, v78 quad_perm:[2,3,0,1] row_mask:0xf bank_mask:0xf bound_ctrl:1
	v_add_f32_e32 v95, v84, v85
	v_pk_fma_f32 v[82:83], v[4:5], v[56:57], v[82:83]
	v_add_f32_dpp v78, v78, v78 row_half_mirror row_mask:0xf bank_mask:0xf bound_ctrl:1
	ds_read_b128 v[6:9], v50 offset:16320
	ds_read_b128 v[18:21], v50 offset:17088
	v_add_f32_dpp v78, v78, v78 row_mirror row_mask:0xf bank_mask:0xf bound_ctrl:1
	v_pk_fma_f32 v[2:3], v[62:63], v[78:79], v[80:81] op_sel_hi:[1,0,1]
	v_pk_fma_f32 v[4:5], v[64:65], v[78:79], v[82:83] op_sel_hi:[1,0,1]
	ds_read_b32 v26, v51 offset:17600
	ds_read_b128 v[14:17], v50 offset:16832
	ds_read_b128 v[22:25], v50 offset:17344
	s_waitcnt lgkmcnt(6)
	v_pk_mul_f32 v[76:77], v[2:3], v[108:109]
	ds_read_b128 v[32:35], v50 offset:17936
	v_pk_fma_f32 v[76:77], v[4:5], v[110:111], v[76:77]
	v_pk_mul_f32 v[80:81], v[116:117], v[124:125] op_sel_hi:[1,0]
	v_add_f32_e32 v78, v76, v77
	v_pk_mul_f32 v[82:83], v[118:119], v[124:125] op_sel_hi:[1,0]
	v_pk_mul_f32 v[84:85], v[70:71], v[2:3]
	v_add_f32_dpp v78, v78, v78 quad_perm:[1,0,3,2] row_mask:0xf bank_mask:0xf bound_ctrl:1
	v_pk_fma_f32 v[84:85], v[72:73], v[4:5], v[84:85]
	v_pk_fma_f32 v[80:81], v[2:3], v[104:105], v[80:81]
	v_add_f32_dpp v78, v78, v78 quad_perm:[2,3,0,1] row_mask:0xf bank_mask:0xf bound_ctrl:1
	v_add_f32_e32 v126, v84, v85
	v_pk_fma_f32 v[82:83], v[4:5], v[106:107], v[82:83]
	v_add_f32_dpp v78, v78, v78 row_half_mirror row_mask:0xf bank_mask:0xf bound_ctrl:1
	ds_read_b128 v[28:31], v50 offset:17680
	ds_read_b128 v[40:43], v50 offset:18448
	v_add_f32_dpp v78, v78, v78 row_mirror row_mask:0xf bank_mask:0xf bound_ctrl:1
	v_pk_fma_f32 v[2:3], v[112:113], v[78:79], v[80:81] op_sel_hi:[1,0,1]
	v_pk_fma_f32 v[4:5], v[114:115], v[78:79], v[82:83] op_sel_hi:[1,0,1]
	ds_read_b32 v48, v51 offset:18960
	ds_read_b128 v[36:39], v50 offset:18192
	ds_read_b128 v[44:47], v50 offset:18704
	s_waitcnt lgkmcnt(6)
	v_pk_mul_f32 v[76:77], v[2:3], v[10:11]
	ds_read_b128 v[58:61], v50 offset:19296
	v_pk_fma_f32 v[76:77], v[4:5], v[12:13], v[76:77]
	v_pk_mul_f32 v[80:81], v[18:19], v[26:27] op_sel_hi:[1,0]
	v_add_f32_e32 v78, v76, v77
	v_pk_mul_f32 v[82:83], v[20:21], v[26:27] op_sel_hi:[1,0]
	v_pk_mul_f32 v[84:85], v[120:121], v[2:3]
	v_add_f32_dpp v78, v78, v78 quad_perm:[1,0,3,2] row_mask:0xf bank_mask:0xf bound_ctrl:1
	v_pk_fma_f32 v[84:85], v[122:123], v[4:5], v[84:85]
	v_pk_fma_f32 v[80:81], v[2:3], v[6:7], v[80:81]
	v_add_f32_dpp v78, v78, v78 quad_perm:[2,3,0,1] row_mask:0xf bank_mask:0xf bound_ctrl:1
	v_add_f32_e32 v127, v84, v85
	v_pk_fma_f32 v[82:83], v[4:5], v[8:9], v[82:83]
	v_add_f32_dpp v78, v78, v78 row_half_mirror row_mask:0xf bank_mask:0xf bound_ctrl:1
	ds_read_b128 v[54:57], v50 offset:19040
	ds_read_b128 v[66:69], v50 offset:19808
	v_add_f32_dpp v78, v78, v78 row_mirror row_mask:0xf bank_mask:0xf bound_ctrl:1
	v_pk_fma_f32 v[2:3], v[14:15], v[78:79], v[80:81] op_sel_hi:[1,0,1]
	v_pk_fma_f32 v[4:5], v[16:17], v[78:79], v[82:83] op_sel_hi:[1,0,1]
	ds_read_b32 v74, v51 offset:20320
	ds_read_b128 v[62:65], v50 offset:19552
	ds_read_b128 v[70:73], v50 offset:20064
	s_waitcnt lgkmcnt(6)
	v_pk_mul_f32 v[76:77], v[2:3], v[32:33]
	ds_read_b128 v[108:111], v50 offset:20656
	v_pk_fma_f32 v[76:77], v[4:5], v[34:35], v[76:77]
	v_pk_mul_f32 v[80:81], v[40:41], v[48:49] op_sel_hi:[1,0]
	v_add_f32_e32 v78, v76, v77
	v_pk_mul_f32 v[82:83], v[42:43], v[48:49] op_sel_hi:[1,0]
	v_pk_mul_f32 v[84:85], v[22:23], v[2:3]
	v_add_f32_dpp v78, v78, v78 quad_perm:[1,0,3,2] row_mask:0xf bank_mask:0xf bound_ctrl:1
	v_pk_fma_f32 v[84:85], v[24:25], v[4:5], v[84:85]
	v_pk_fma_f32 v[80:81], v[2:3], v[28:29], v[80:81]
	v_add_f32_dpp v78, v78, v78 quad_perm:[2,3,0,1] row_mask:0xf bank_mask:0xf bound_ctrl:1
	v_add_f32_e32 v128, v84, v85
	v_pk_fma_f32 v[82:83], v[4:5], v[30:31], v[82:83]
	v_add_f32_dpp v78, v78, v78 row_half_mirror row_mask:0xf bank_mask:0xf bound_ctrl:1
	ds_read_b128 v[104:107], v50 offset:20400
	ds_read_b128 v[116:119], v50 offset:21168
	v_add_f32_dpp v78, v78, v78 row_mirror row_mask:0xf bank_mask:0xf bound_ctrl:1
	v_pk_fma_f32 v[2:3], v[36:37], v[78:79], v[80:81] op_sel_hi:[1,0,1]
	v_pk_fma_f32 v[4:5], v[38:39], v[78:79], v[82:83] op_sel_hi:[1,0,1]
	ds_read_b32 v124, v51 offset:21680
	ds_read_b128 v[112:115], v50 offset:20912
	ds_read_b128 v[120:123], v50 offset:21424
	s_waitcnt lgkmcnt(6)
; #define LAS __attribute__((address_space(3)))
; __device__ __forceinline__ float allred16(float x) { x += dpp_f<0xB1>(x); x += dpp_f<0x4E>(x); x += dpp_f<0x141>(x); x += dpp_f<0x140>(x); return x; }
; #define SCAN_BAR() do { asm volatile("s_waitcnt lgkmcnt(0)" ::: "memory"); __builtin_amdgcn_s_barrier(); asm volatile("" ::: "memory"); } while (0)
; __device__ __forceinline__ void phase_scan(const Args& a, int l, LAS unsigned char* lds) {
;     ...
;                     for (int t = 0; t < TC; ++t) {
;                         f32x4 nw = w, nkk = kk, nbv = bv, nkv = kv, nwr = wr; float nvv = vv;
;                         if (t + 1 < TC) { const LAS float* p = tb + (t + 1) * TOKF;
;                             nw = *(const LAS f32x4*)(p + 4 * j); nkk = *(const LAS f32x4*)(p + 64 + 4 * j); nbv = *(const LAS f32x4*)(p + 128 + 4 * j);
;                             nkv = *(const LAS f32x4*)(p + 192 + 4 * j); nwr = *(const LAS f32x4*)(p + 256 + 4 * j); nvv = p[320 + rowl]; }
;                         f32x2 ta = Sl * kk.lo; ta = Sh * kk.hi + ta;
;                         float pa = ta.x + ta.y;
;                         const f32x2 tl = Sl * w.lo + kv.lo * vv, th = Sh * w.hi + kv.hi * vv;
;                         pa = allred16(pa);
;                         Sl = bv.lo * pa + tl;
;                         Sh = bv.hi * pa + th;
;                         f32x2 ty = Sl * wr.lo; ty = Sh * wr.hi + ty;
;                         float y = ty.x + ty.y;
;                         y = allred16(y);
;                         yv = (j == t) ? y : yv;
;                         w = nw; kk = nkk; bv = nbv; kv = nkv; wr = nwr; vv = nvv;
;                     }
;                     yb[j * 16 + rowl] = yv;
;                 }
;                 SCAN_BAR();
;             }
	v_pk_mul_f32 v[76:77], v[2:3], v[58:59]
	s_nop 0
	v_pk_fma_f32 v[76:77], v[4:5], v[60:61], v[76:77]
	v_pk_mul_f32 v[80:81], v[66:67], v[74:75] op_sel_hi:[1,0]
	v_add_f32_e32 v78, v76, v77
	v_pk_mul_f32 v[82:83], v[68:69], v[74:75] op_sel_hi:[1,0]
	v_pk_mul_f32 v[84:85], v[44:45], v[2:3]
	v_add_f32_dpp v78, v78, v78 quad_perm:[1,0,3,2] row_mask:0xf bank_mask:0xf bound_ctrl:1
	v_pk_fma_f32 v[84:85], v[46:47], v[4:5], v[84:85]
	v_pk_fma_f32 v[80:81], v[2:3], v[54:55], v[80:81]
	v_add_f32_dpp v78, v78, v78 quad_perm:[2,3,0,1] row_mask:0xf bank_mask:0xf bound_ctrl:1
	v_add_f32_e32 v129, v84, v85
	v_pk_fma_f32 v[82:83], v[4:5], v[56:57], v[82:83]
	v_add_f32_dpp v78, v78, v78 row_half_mirror row_mask:0xf bank_mask:0xf bound_ctrl:1
	s_nop 1
	v_add_f32_dpp v78, v78, v78 row_mirror row_mask:0xf bank_mask:0xf bound_ctrl:1
	v_pk_fma_f32 v[2:3], v[62:63], v[78:79], v[80:81] op_sel_hi:[1,0,1]
	v_pk_fma_f32 v[4:5], v[64:65], v[78:79], v[82:83] op_sel_hi:[1,0,1]
	s_waitcnt lgkmcnt(0)
	v_pk_mul_f32 v[76:77], v[2:3], v[108:109]
	s_nop 0
	v_pk_fma_f32 v[76:77], v[4:5], v[110:111], v[76:77]
	v_pk_mul_f32 v[80:81], v[116:117], v[124:125] op_sel_hi:[1,0]
	v_add_f32_e32 v78, v76, v77
	v_pk_mul_f32 v[82:83], v[118:119], v[124:125] op_sel_hi:[1,0]
	v_pk_mul_f32 v[84:85], v[70:71], v[2:3]
	v_add_f32_dpp v78, v78, v78 quad_perm:[1,0,3,2] row_mask:0xf bank_mask:0xf bound_ctrl:1
	v_pk_fma_f32 v[84:85], v[72:73], v[4:5], v[84:85]
	v_pk_fma_f32 v[80:81], v[2:3], v[104:105], v[80:81]
	v_add_f32_dpp v78, v78, v78 quad_perm:[2,3,0,1] row_mask:0xf bank_mask:0xf bound_ctrl:1
	v_add_f32_e32 v130, v84, v85
	v_pk_fma_f32 v[82:83], v[4:5], v[106:107], v[82:83]
	v_add_f32_dpp v78, v78, v78 row_half_mirror row_mask:0xf bank_mask:0xf bound_ctrl:1
	s_nop 1
	v_add_f32_dpp v78, v78, v78 row_mirror row_mask:0xf bank_mask:0xf bound_ctrl:1
	v_pk_fma_f32 v[2:3], v[112:113], v[78:79], v[80:81] op_sel_hi:[1,0,1]
	v_pk_fma_f32 v[4:5], v[114:115], v[78:79], v[82:83] op_sel_hi:[1,0,1]
	v_pk_mul_f32 v[84:85], v[120:121], v[2:3]
	v_lshl_add_u32 v52, s38, 2, v193
	v_pk_fma_f32 v[84:85], v[122:123], v[4:5], v[84:85]
	s_nop 0
	v_add_f32_e32 v131, v84, v85
	v_add_f32_dpp v86, v86, v86 row_shl:8 row_mask:0xf bank_mask:0x3 bound_ctrl:1
	v_add_f32_dpp v86, v94, v94 row_shr:8 row_mask:0xf bank_mask:0xc bound_ctrl:1
	v_add_f32_dpp v87, v87, v87 row_shl:8 row_mask:0xf bank_mask:0x3 bound_ctrl:1
	v_add_f32_dpp v87, v95, v95 row_shr:8 row_mask:0xf bank_mask:0xc bound_ctrl:1
	v_add_f32_dpp v88, v88, v88 row_shl:8 row_mask:0xf bank_mask:0x3 bound_ctrl:1
	v_add_f32_dpp v88, v126, v126 row_shr:8 row_mask:0xf bank_mask:0xc bound_ctrl:1
	v_add_f32_dpp v89, v89, v89 row_shl:8 row_mask:0xf bank_mask:0x3 bound_ctrl:1
	v_add_f32_dpp v89, v127, v127 row_shr:8 row_mask:0xf bank_mask:0xc bound_ctrl:1
	v_add_f32_dpp v90, v90, v90 row_shl:8 row_mask:0xf bank_mask:0x3 bound_ctrl:1
	v_add_f32_dpp v90, v128, v128 row_shr:8 row_mask:0xf bank_mask:0xc bound_ctrl:1
	v_add_f32_dpp v91, v91, v91 row_shl:8 row_mask:0xf bank_mask:0x3 bound_ctrl:1
	v_add_f32_dpp v91, v129, v129 row_shr:8 row_mask:0xf bank_mask:0xc bound_ctrl:1
	v_add_f32_dpp v92, v92, v92 row_shl:8 row_mask:0xf bank_mask:0x3 bound_ctrl:1
	v_add_f32_dpp v92, v130, v130 row_shr:8 row_mask:0xf bank_mask:0xc bound_ctrl:1
	v_add_f32_dpp v93, v93, v93 row_shl:8 row_mask:0xf bank_mask:0x3 bound_ctrl:1
	v_add_f32_dpp v93, v131, v131 row_shr:8 row_mask:0xf bank_mask:0xc bound_ctrl:1
	v_cmp_ne_u32_e32 vcc, 0, v138
	v_add_f32_dpp v86, v86, v86 row_shl:4 row_mask:0xf bank_mask:0x5 bound_ctrl:1
	v_add_f32_dpp v86, v90, v90 row_shr:4 row_mask:0xf bank_mask:0xa bound_ctrl:1
	v_add_f32_dpp v87, v87, v87 row_shl:4 row_mask:0xf bank_mask:0x5 bound_ctrl:1
	v_add_f32_dpp v87, v91, v91 row_shr:4 row_mask:0xf bank_mask:0xa bound_ctrl:1
	v_add_f32_dpp v88, v88, v88 row_shl:4 row_mask:0xf bank_mask:0x5 bound_ctrl:1
	v_add_f32_dpp v88, v92, v92 row_shr:4 row_mask:0xf bank_mask:0xa bound_ctrl:1
	v_add_f32_dpp v89, v89, v89 row_shl:4 row_mask:0xf bank_mask:0x5 bound_ctrl:1
	v_add_f32_dpp v89, v93, v93 row_shr:4 row_mask:0xf bank_mask:0xa bound_ctrl:1
	v_add_f32_dpp v86, v86, v86 quad_perm:[2,3,0,1] row_mask:0xf bank_mask:0xf bound_ctrl:1
	v_add_f32_dpp v87, v87, v87 quad_perm:[2,3,0,1] row_mask:0xf bank_mask:0xf bound_ctrl:1
	v_add_f32_dpp v88, v88, v88 quad_perm:[2,3,0,1] row_mask:0xf bank_mask:0xf bound_ctrl:1
	v_add_f32_dpp v89, v89, v89 quad_perm:[2,3,0,1] row_mask:0xf bank_mask:0xf bound_ctrl:1
	v_cndmask_b32_e32 v86, v86, v88, vcc
	v_cndmask_b32_e32 v87, v87, v89, vcc
	v_cmp_ne_u32_e32 vcc, 0, v142
	v_add_f32_dpp v86, v86, v86 quad_perm:[1,0,3,2] row_mask:0xf bank_mask:0xf bound_ctrl:1
	v_add_f32_dpp v87, v87, v87 quad_perm:[1,0,3,2] row_mask:0xf bank_mask:0xf bound_ctrl:1
	v_cndmask_b32_e32 v86, v86, v87, vcc
	ds_write_b32 v52, v86
	s_branch .LBB0_167
.Lscan_warm_bar:
	s_waitcnt lgkmcnt(0)
	s_barrier
	s_branch .LBB0_167
.Lscan_exit_bar:
	s_waitcnt lgkmcnt(0)
	s_barrier
.LBB0_170:
	s_setprio 0
	s_mov_b64 s[0:1], 0
